# pool sample: window loads (up to 15 dependent-free rows) issued together, summed in the same order
# baseline (speedup 1.0000x reference)
; DI void pool_phase(ArgsP a, int l, const float* XA, bf16_t* Dm, int gt  , int NT  , int lo, int hi  , bool do_sample) {
;     ...
;     if (do_sample) for (int idx = gt; idx < MS * 128; idx += NT) {
;         const int row = MP + (idx >> 7), c4 = (idx & 127) * 4, w = 2 << (c4 >> 7);
;         const f32x4 x = *(const f32x4*)(XA + (size_t)row * 512 + c4); f32x4 sum = x;
;         const int rs = row - MP, bs = rs >> 2, t = rs & 3;
;         for (int s = 1; s < w; ++s) { const int pos = t - s;
;             sum += pos >= 0 ? *(const f32x4*)(XA + (size_t)(row - s) * 512 + c4) : *(const f32x4*)(a->in[4] + ((size_t)(l * 128 + bs) * 15 + 15 + pos) * 512 + c4); }
.LBB0_873:
	v_ashrrev_i32_e32 v4, 7, v114
	v_add_u32_e32 v6, 0x4000, v4
	v_lshlrev_b32_e32 v5, 2, v114
	v_ashrrev_i32_e32 v7, 31, v6
	v_and_b32_e32 v8, 0x1fc, v5
	v_lshlrev_b64 v[0:1], 11, v[6:7]
	v_lshl_add_u64 v[0:1], s[2:3], 0, v[0:1]
	v_lshlrev_b32_e32 v96, 2, v8
	v_lshl_add_u64 v[0:1], v[0:1], 0, v[96:97]
	global_load_dwordx4 v[0:3], v[0:1], off
	v_bfe_u32 v5, v5, 7, 2
	v_lshlrev_b32_e64 v9, v5, 2
	v_ashrrev_i32_e32 v5, 9, v114
	v_add_u32_e32 v5, s87, v5
	v_mad_i64_i32 v[12:13], s[10:11], v5, 15, 0
	v_mad_i64_i32 v[14:15], s[10:11], v5, 15, 15
	v_ashrrev_i32_e32 v5, 31, v4
	s_mov_b64 s[10:11], 0x3fff
	v_lshlrev_b64 v[10:11], 9, v[6:7]
	v_and_b32_e32 v22, 3, v4
	v_lshl_add_u64 v[16:17], v[4:5], 0, s[10:11]
	s_load_dwordx2 s[16:17], s[34:35], 0x20
	s_mov_b64 s[10:11], exec
	s_waitcnt lgkmcnt(0)
	v_cmp_lt_u32_e32 vcc, 1, v9
	s_and_b64 exec, exec, vcc
	s_cbranch_execz .Lpb_issued
	v_add_u32_e32 v18, -1, v22
	v_ashrrev_i32_e32 v19, 31, v18
	v_lshl_add_u64 v[20:21], v[14:15], 0, v[18:19]
	v_lshlrev_b64 v[20:21], 11, v[20:21]
	v_lshl_add_u64 v[20:21], s[16:17], 0, v[20:21]
	v_lshl_add_u64 v[84:85], v[16:17], 0, 0
	v_lshlrev_b64 v[84:85], 11, v[84:85]
	v_lshl_add_u64 v[84:85], s[2:3], 0, v[84:85]
	v_cmp_gt_i32_e32 vcc, 0, v18
	s_nop 1
	v_cndmask_b32_e32 v20, v84, v20, vcc
	v_cndmask_b32_e32 v21, v85, v21, vcc
	v_lshl_add_u64 v[20:21], v[20:21], 0, v[96:97]
	global_load_dwordx4 v[24:27], v[20:21], off
	v_cmp_lt_u32_e32 vcc, 2, v9
	s_and_b64 exec, exec, vcc
	s_cbranch_execz .Lpb_issued
	v_add_u32_e32 v18, -2, v22
	v_ashrrev_i32_e32 v19, 31, v18
	v_lshl_add_u64 v[20:21], v[14:15], 0, v[18:19]
	v_lshlrev_b64 v[20:21], 11, v[20:21]
	v_lshl_add_u64 v[20:21], s[16:17], 0, v[20:21]
	v_lshl_add_u64 v[84:85], v[16:17], 0, -1
	v_lshlrev_b64 v[84:85], 11, v[84:85]
	v_lshl_add_u64 v[84:85], s[2:3], 0, v[84:85]
	v_cmp_gt_i32_e32 vcc, 0, v18
	s_nop 1
	v_cndmask_b32_e32 v20, v84, v20, vcc
	v_cndmask_b32_e32 v21, v85, v21, vcc
	v_lshl_add_u64 v[20:21], v[20:21], 0, v[96:97]
	global_load_dwordx4 v[28:31], v[20:21], off
	v_cmp_lt_u32_e32 vcc, 3, v9
	s_and_b64 exec, exec, vcc
	s_cbranch_execz .Lpb_issued
	v_add_u32_e32 v18, -3, v22
	v_ashrrev_i32_e32 v19, 31, v18
	v_lshl_add_u64 v[20:21], v[14:15], 0, v[18:19]
	v_lshlrev_b64 v[20:21], 11, v[20:21]
	v_lshl_add_u64 v[20:21], s[16:17], 0, v[20:21]
	v_lshl_add_u64 v[84:85], v[16:17], 0, -2
	v_lshlrev_b64 v[84:85], 11, v[84:85]
	v_lshl_add_u64 v[84:85], s[2:3], 0, v[84:85]
	v_cmp_gt_i32_e32 vcc, 0, v18
	s_nop 1
	v_cndmask_b32_e32 v20, v84, v20, vcc
	v_cndmask_b32_e32 v21, v85, v21, vcc
	v_lshl_add_u64 v[20:21], v[20:21], 0, v[96:97]
	global_load_dwordx4 v[32:35], v[20:21], off
	v_cmp_lt_u32_e32 vcc, 4, v9
	s_and_b64 exec, exec, vcc
	s_cbranch_execz .Lpb_issued
	v_add_u32_e32 v18, -4, v22
	v_ashrrev_i32_e32 v19, 31, v18
	v_lshl_add_u64 v[20:21], v[14:15], 0, v[18:19]
	v_lshlrev_b64 v[20:21], 11, v[20:21]
	v_lshl_add_u64 v[20:21], s[16:17], 0, v[20:21]
	v_lshl_add_u64 v[84:85], v[16:17], 0, -3
	v_lshlrev_b64 v[84:85], 11, v[84:85]
	v_lshl_add_u64 v[84:85], s[2:3], 0, v[84:85]
	v_cmp_gt_i32_e32 vcc, 0, v18
	s_nop 1
	v_cndmask_b32_e32 v20, v84, v20, vcc
	v_cndmask_b32_e32 v21, v85, v21, vcc
	v_lshl_add_u64 v[20:21], v[20:21], 0, v[96:97]
	global_load_dwordx4 v[36:39], v[20:21], off
	v_cmp_lt_u32_e32 vcc, 5, v9
	s_and_b64 exec, exec, vcc
	s_cbranch_execz .Lpb_issued
	v_add_u32_e32 v18, -5, v22
	v_ashrrev_i32_e32 v19, 31, v18
	v_lshl_add_u64 v[20:21], v[14:15], 0, v[18:19]
	v_lshlrev_b64 v[20:21], 11, v[20:21]
	v_lshl_add_u64 v[20:21], s[16:17], 0, v[20:21]
	v_lshl_add_u64 v[84:85], v[16:17], 0, -4
	v_lshlrev_b64 v[84:85], 11, v[84:85]
	v_lshl_add_u64 v[84:85], s[2:3], 0, v[84:85]
	v_cmp_gt_i32_e32 vcc, 0, v18
	s_nop 1
	v_cndmask_b32_e32 v20, v84, v20, vcc
	v_cndmask_b32_e32 v21, v85, v21, vcc
	v_lshl_add_u64 v[20:21], v[20:21], 0, v[96:97]
	global_load_dwordx4 v[40:43], v[20:21], off
	v_cmp_lt_u32_e32 vcc, 6, v9
	s_and_b64 exec, exec, vcc
	s_cbranch_execz .Lpb_issued
	v_add_u32_e32 v18, -6, v22
	v_ashrrev_i32_e32 v19, 31, v18
	v_lshl_add_u64 v[20:21], v[14:15], 0, v[18:19]
	v_lshlrev_b64 v[20:21], 11, v[20:21]
	v_lshl_add_u64 v[20:21], s[16:17], 0, v[20:21]
	v_lshl_add_u64 v[84:85], v[16:17], 0, -5
	v_lshlrev_b64 v[84:85], 11, v[84:85]
	v_lshl_add_u64 v[84:85], s[2:3], 0, v[84:85]
	v_cmp_gt_i32_e32 vcc, 0, v18
	s_nop 1
	v_cndmask_b32_e32 v20, v84, v20, vcc
	v_cndmask_b32_e32 v21, v85, v21, vcc
	v_lshl_add_u64 v[20:21], v[20:21], 0, v[96:97]
	global_load_dwordx4 v[44:47], v[20:21], off
	v_cmp_lt_u32_e32 vcc, 7, v9
	s_and_b64 exec, exec, vcc
	s_cbranch_execz .Lpb_issued
	v_add_u32_e32 v18, -7, v22
	v_ashrrev_i32_e32 v19, 31, v18
	v_lshl_add_u64 v[20:21], v[14:15], 0, v[18:19]
	v_lshlrev_b64 v[20:21], 11, v[20:21]
	v_lshl_add_u64 v[20:21], s[16:17], 0, v[20:21]
	v_lshl_add_u64 v[84:85], v[16:17], 0, -6
	v_lshlrev_b64 v[84:85], 11, v[84:85]
	v_lshl_add_u64 v[84:85], s[2:3], 0, v[84:85]
	v_cmp_gt_i32_e32 vcc, 0, v18
	s_nop 1
	v_cndmask_b32_e32 v20, v84, v20, vcc
	v_cndmask_b32_e32 v21, v85, v21, vcc
	v_lshl_add_u64 v[20:21], v[20:21], 0, v[96:97]
	global_load_dwordx4 v[48:51], v[20:21], off
	v_cmp_lt_u32_e32 vcc, 8, v9
	s_and_b64 exec, exec, vcc
	s_cbranch_execz .Lpb_issued
	v_add_u32_e32 v18, -8, v22
	v_ashrrev_i32_e32 v19, 31, v18
	v_lshl_add_u64 v[20:21], v[14:15], 0, v[18:19]
	v_lshlrev_b64 v[20:21], 11, v[20:21]
	v_lshl_add_u64 v[20:21], s[16:17], 0, v[20:21]
	v_lshl_add_u64 v[84:85], v[16:17], 0, -7
	v_lshlrev_b64 v[84:85], 11, v[84:85]
	v_lshl_add_u64 v[84:85], s[2:3], 0, v[84:85]
	v_cmp_gt_i32_e32 vcc, 0, v18
	s_nop 1
	v_cndmask_b32_e32 v20, v84, v20, vcc
	v_cndmask_b32_e32 v21, v85, v21, vcc
	v_lshl_add_u64 v[20:21], v[20:21], 0, v[96:97]
	global_load_dwordx4 v[52:55], v[20:21], off
	v_cmp_lt_u32_e32 vcc, 9, v9
	s_and_b64 exec, exec, vcc
	s_cbranch_execz .Lpb_issued
; __device__ __forceinline__ void st_bf4(bf16_t* p, const f32x4 v) { u32x2 w; w.x = cvt_pk_bf16(v[0], v[1]); w.y = cvt_pk_bf16(v[2], v[3]); *(u32x2*)p = w; }
; DI void pool_phase(ArgsP a, int l, const float* XA, bf16_t* Dm, int gt  , int NT  , int lo, int hi  , bool do_sample) {
;     ...
;     if (do_sample) for (int idx = gt; idx < MS * 128; idx += NT) {
;         const int row = MP + (idx >> 7), c4 = (idx & 127) * 4, w = 2 << (c4 >> 7);
;         const f32x4 x = *(const f32x4*)(XA + (size_t)row * 512 + c4); f32x4 sum = x;
;         const int rs = row - MP, bs = rs >> 2, t = rs & 3;
;         for (int s = 1; s < w; ++s) { const int pos = t - s;
;             sum += pos >= 0 ? *(const f32x4*)(XA + (size_t)(row - s) * 512 + c4) : *(const f32x4*)(a->in[4] + ((size_t)(l * 128 + bs) * 15 + 15 + pos) * 512 + c4); }
;         *(f32x4*)(a->out + OFF_PS + ((size_t)(l * 128 + bs) * 15 + 11 + t) * 512 + c4) = x;
;         st_bf4(Dm + (size_t)row * 512 + c4, sum * (1.f / (float)w) - x);
	v_add_u32_e32 v18, -9, v22
	v_ashrrev_i32_e32 v19, 31, v18
	v_lshl_add_u64 v[20:21], v[14:15], 0, v[18:19]
	v_lshlrev_b64 v[20:21], 11, v[20:21]
	v_lshl_add_u64 v[20:21], s[16:17], 0, v[20:21]
	v_lshl_add_u64 v[84:85], v[16:17], 0, -8
	v_lshlrev_b64 v[84:85], 11, v[84:85]
	v_lshl_add_u64 v[84:85], s[2:3], 0, v[84:85]
	v_cmp_gt_i32_e32 vcc, 0, v18
	s_nop 1
	v_cndmask_b32_e32 v20, v84, v20, vcc
	v_cndmask_b32_e32 v21, v85, v21, vcc
	v_lshl_add_u64 v[20:21], v[20:21], 0, v[96:97]
	global_load_dwordx4 v[56:59], v[20:21], off
	v_cmp_lt_u32_e32 vcc, 10, v9
	s_and_b64 exec, exec, vcc
	s_cbranch_execz .Lpb_issued
	v_add_u32_e32 v18, -10, v22
	v_ashrrev_i32_e32 v19, 31, v18
	v_lshl_add_u64 v[20:21], v[14:15], 0, v[18:19]
	v_lshlrev_b64 v[20:21], 11, v[20:21]
	v_lshl_add_u64 v[20:21], s[16:17], 0, v[20:21]
	v_lshl_add_u64 v[84:85], v[16:17], 0, -9
	v_lshlrev_b64 v[84:85], 11, v[84:85]
	v_lshl_add_u64 v[84:85], s[2:3], 0, v[84:85]
	v_cmp_gt_i32_e32 vcc, 0, v18
	s_nop 1
	v_cndmask_b32_e32 v20, v84, v20, vcc
	v_cndmask_b32_e32 v21, v85, v21, vcc
	v_lshl_add_u64 v[20:21], v[20:21], 0, v[96:97]
	global_load_dwordx4 v[60:63], v[20:21], off
	v_cmp_lt_u32_e32 vcc, 11, v9
	s_and_b64 exec, exec, vcc
	s_cbranch_execz .Lpb_issued
	v_add_u32_e32 v18, -11, v22
	v_ashrrev_i32_e32 v19, 31, v18
	v_lshl_add_u64 v[20:21], v[14:15], 0, v[18:19]
	v_lshlrev_b64 v[20:21], 11, v[20:21]
	v_lshl_add_u64 v[20:21], s[16:17], 0, v[20:21]
	v_lshl_add_u64 v[84:85], v[16:17], 0, -10
	v_lshlrev_b64 v[84:85], 11, v[84:85]
	v_lshl_add_u64 v[84:85], s[2:3], 0, v[84:85]
	v_cmp_gt_i32_e32 vcc, 0, v18
	s_nop 1
	v_cndmask_b32_e32 v20, v84, v20, vcc
	v_cndmask_b32_e32 v21, v85, v21, vcc
	v_lshl_add_u64 v[20:21], v[20:21], 0, v[96:97]
	global_load_dwordx4 v[64:67], v[20:21], off
	v_cmp_lt_u32_e32 vcc, 12, v9
	s_and_b64 exec, exec, vcc
	s_cbranch_execz .Lpb_issued
	v_add_u32_e32 v18, -12, v22
	v_ashrrev_i32_e32 v19, 31, v18
	v_lshl_add_u64 v[20:21], v[14:15], 0, v[18:19]
	v_lshlrev_b64 v[20:21], 11, v[20:21]
	v_lshl_add_u64 v[20:21], s[16:17], 0, v[20:21]
	v_lshl_add_u64 v[84:85], v[16:17], 0, -11
	v_lshlrev_b64 v[84:85], 11, v[84:85]
	v_lshl_add_u64 v[84:85], s[2:3], 0, v[84:85]
	v_cmp_gt_i32_e32 vcc, 0, v18
	s_nop 1
	v_cndmask_b32_e32 v20, v84, v20, vcc
	v_cndmask_b32_e32 v21, v85, v21, vcc
	v_lshl_add_u64 v[20:21], v[20:21], 0, v[96:97]
	global_load_dwordx4 v[68:71], v[20:21], off
	v_cmp_lt_u32_e32 vcc, 13, v9
	s_and_b64 exec, exec, vcc
	s_cbranch_execz .Lpb_issued
	v_add_u32_e32 v18, -13, v22
	v_ashrrev_i32_e32 v19, 31, v18
	v_lshl_add_u64 v[20:21], v[14:15], 0, v[18:19]
	v_lshlrev_b64 v[20:21], 11, v[20:21]
	v_lshl_add_u64 v[20:21], s[16:17], 0, v[20:21]
	v_lshl_add_u64 v[84:85], v[16:17], 0, -12
	v_lshlrev_b64 v[84:85], 11, v[84:85]
	v_lshl_add_u64 v[84:85], s[2:3], 0, v[84:85]
	v_cmp_gt_i32_e32 vcc, 0, v18
	s_nop 1
	v_cndmask_b32_e32 v20, v84, v20, vcc
	v_cndmask_b32_e32 v21, v85, v21, vcc
	v_lshl_add_u64 v[20:21], v[20:21], 0, v[96:97]
	global_load_dwordx4 v[72:75], v[20:21], off
	v_cmp_lt_u32_e32 vcc, 14, v9
	s_and_b64 exec, exec, vcc
	s_cbranch_execz .Lpb_issued
	v_add_u32_e32 v18, -14, v22
	v_ashrrev_i32_e32 v19, 31, v18
	v_lshl_add_u64 v[20:21], v[14:15], 0, v[18:19]
	v_lshlrev_b64 v[20:21], 11, v[20:21]
	v_lshl_add_u64 v[20:21], s[16:17], 0, v[20:21]
	v_lshl_add_u64 v[84:85], v[16:17], 0, -13
	v_lshlrev_b64 v[84:85], 11, v[84:85]
	v_lshl_add_u64 v[84:85], s[2:3], 0, v[84:85]
	v_cmp_gt_i32_e32 vcc, 0, v18
	s_nop 1
	v_cndmask_b32_e32 v20, v84, v20, vcc
	v_cndmask_b32_e32 v21, v85, v21, vcc
	v_lshl_add_u64 v[20:21], v[20:21], 0, v[96:97]
	global_load_dwordx4 v[76:79], v[20:21], off
	v_cmp_lt_u32_e32 vcc, 15, v9
	s_and_b64 exec, exec, vcc
	s_cbranch_execz .Lpb_issued
	v_add_u32_e32 v18, -15, v22
	v_ashrrev_i32_e32 v19, 31, v18
	v_lshl_add_u64 v[20:21], v[14:15], 0, v[18:19]
	v_lshlrev_b64 v[20:21], 11, v[20:21]
	v_lshl_add_u64 v[20:21], s[16:17], 0, v[20:21]
	v_lshl_add_u64 v[84:85], v[16:17], 0, -14
	v_lshlrev_b64 v[84:85], 11, v[84:85]
	v_lshl_add_u64 v[84:85], s[2:3], 0, v[84:85]
	v_cmp_gt_i32_e32 vcc, 0, v18
	s_nop 1
	v_cndmask_b32_e32 v20, v84, v20, vcc
	v_cndmask_b32_e32 v21, v85, v21, vcc
	v_lshl_add_u64 v[20:21], v[20:21], 0, v[96:97]
	global_load_dwordx4 v[80:83], v[20:21], off
.Lpb_issued:
	s_waitcnt vmcnt(0)
	s_mov_b64 exec, s[10:11]
	v_mov_b64_e32 v[6:7], v[2:3]
	v_mov_b64_e32 v[4:5], v[0:1]
	v_cmp_lt_u32_e32 vcc, 1, v9
	s_and_b64 exec, exec, vcc
	s_cbranch_execz .Lpb_done
	v_pk_add_f32 v[6:7], v[6:7], v[26:27]
	v_pk_add_f32 v[4:5], v[4:5], v[24:25]
	v_cmp_lt_u32_e32 vcc, 2, v9
	s_and_b64 exec, exec, vcc
	s_cbranch_execz .Lpb_done
	v_pk_add_f32 v[6:7], v[6:7], v[30:31]
	v_pk_add_f32 v[4:5], v[4:5], v[28:29]
	v_cmp_lt_u32_e32 vcc, 3, v9
	s_and_b64 exec, exec, vcc
	s_cbranch_execz .Lpb_done
	v_pk_add_f32 v[6:7], v[6:7], v[34:35]
	v_pk_add_f32 v[4:5], v[4:5], v[32:33]
	v_cmp_lt_u32_e32 vcc, 4, v9
	s_and_b64 exec, exec, vcc
	s_cbranch_execz .Lpb_done
	v_pk_add_f32 v[6:7], v[6:7], v[38:39]
	v_pk_add_f32 v[4:5], v[4:5], v[36:37]
	v_cmp_lt_u32_e32 vcc, 5, v9
	s_and_b64 exec, exec, vcc
	s_cbranch_execz .Lpb_done
	v_pk_add_f32 v[6:7], v[6:7], v[42:43]
	v_pk_add_f32 v[4:5], v[4:5], v[40:41]
	v_cmp_lt_u32_e32 vcc, 6, v9
	s_and_b64 exec, exec, vcc
	s_cbranch_execz .Lpb_done
	v_pk_add_f32 v[6:7], v[6:7], v[46:47]
	v_pk_add_f32 v[4:5], v[4:5], v[44:45]
	v_cmp_lt_u32_e32 vcc, 7, v9
	s_and_b64 exec, exec, vcc
	s_cbranch_execz .Lpb_done
	v_pk_add_f32 v[6:7], v[6:7], v[50:51]
	v_pk_add_f32 v[4:5], v[4:5], v[48:49]
	v_cmp_lt_u32_e32 vcc, 8, v9
	s_and_b64 exec, exec, vcc
	s_cbranch_execz .Lpb_done
	v_pk_add_f32 v[6:7], v[6:7], v[54:55]
	v_pk_add_f32 v[4:5], v[4:5], v[52:53]
	v_cmp_lt_u32_e32 vcc, 9, v9
	s_and_b64 exec, exec, vcc
	s_cbranch_execz .Lpb_done
	v_pk_add_f32 v[6:7], v[6:7], v[58:59]
	v_pk_add_f32 v[4:5], v[4:5], v[56:57]
	v_cmp_lt_u32_e32 vcc, 10, v9
	s_and_b64 exec, exec, vcc
	s_cbranch_execz .Lpb_done
	v_pk_add_f32 v[6:7], v[6:7], v[62:63]
	v_pk_add_f32 v[4:5], v[4:5], v[60:61]
	v_cmp_lt_u32_e32 vcc, 11, v9
	s_and_b64 exec, exec, vcc
	s_cbranch_execz .Lpb_done
	v_pk_add_f32 v[6:7], v[6:7], v[66:67]
	v_pk_add_f32 v[4:5], v[4:5], v[64:65]
	v_cmp_lt_u32_e32 vcc, 12, v9
	s_and_b64 exec, exec, vcc
	s_cbranch_execz .Lpb_done
	v_pk_add_f32 v[6:7], v[6:7], v[70:71]
	v_pk_add_f32 v[4:5], v[4:5], v[68:69]
	v_cmp_lt_u32_e32 vcc, 13, v9
	s_and_b64 exec, exec, vcc
	s_cbranch_execz .Lpb_done
	v_pk_add_f32 v[6:7], v[6:7], v[74:75]
	v_pk_add_f32 v[4:5], v[4:5], v[72:73]
	v_cmp_lt_u32_e32 vcc, 14, v9
	s_and_b64 exec, exec, vcc
	s_cbranch_execz .Lpb_done
	v_pk_add_f32 v[6:7], v[6:7], v[78:79]
	v_pk_add_f32 v[4:5], v[4:5], v[76:77]
	v_cmp_lt_u32_e32 vcc, 15, v9
	s_and_b64 exec, exec, vcc
	s_cbranch_execz .Lpb_done
	v_pk_add_f32 v[6:7], v[6:7], v[82:83]
	v_pk_add_f32 v[4:5], v[4:5], v[80:81]
.Lpb_done:
	s_mov_b64 exec, s[10:11]
	s_branch .LBB0_872
